# prompt attention: SIMD partner waves take the VALU-only softmax block on opposite sides of the step-closing barrier (waves 4-7 before, 0-3 after) to leave the barrier out of phase
# baseline (speedup 1.0000x reference)
; #define SBAR() __builtin_amdgcn_sched_barrier(0)
; __device__ __forceinline__ int v_st(int k, int c) { const int kk = (k & ~0xC) | ((k & 4) << 1) | ((k & 8) >> 1); return ((kk >> 3) * 4 + (c >> 5)) * 512 + ((kk & 7) * 32 + (c & 31)) * 2; }
; __device__ __forceinline__ int v_rd_base(int lane) { return ((lane & 3) << 3) | (((lane >> 2) & 3) << 6) | (((lane >> 4) & 1) << 5) | (((lane >> 5) & 1) << 8); }
; __device__ __forceinline__ int otid() {
;     const unsigned hw = (unsigned)__builtin_amdgcn_s_getreg((5 << 11) | 4) & 63u;
;     int w = ((volatile __attribute__((address_space(3))) int*)((__attribute__((address_space(3))) unsigned char*)g_lds + LDS_WIDTAB))[hw];
;     w = __builtin_amdgcn_readfirstlane(w);
;     int l; asm volatile("v_mbcnt_lo_u32_b32 %0, -1, 0" : "=v"(l)); asm volatile("v_mbcnt_hi_u32_b32 %0, -1, %0" : "+v"(l));
;     return w * 64 + l;
; }
; template <class TIn, class TOut>
; __device__ __forceinline__ void causal_swa_block(const BlockRef<TIn, TOut>& cur, const BlockRef<TIn, TOut>& nxt, int skv, int W, char* lds, Seam<TIn>& S) {
;     ...
;     const int tid = otid(), wid = __builtin_amdgcn_readfirstlane(tid >> 6), lane = tid & 63, r32 = lane & 31, hi = lane >> 5;
;     const int j_lo = swa_jlo(cur.P0, W);
;     int j_hi = (cur.P0 + QB - 1) / KVBLK + 1; if (j_hi > skv / KVBLK) j_hi = skv / KVBLK;
;     const int NT = j_hi - j_lo;
;     const int kbn = swa_jlo(nxt.P0, W) * KVBLK;
;     const int qlo = cur.P0 + wid * QBLK, qm = qlo + r32 - 4 * hi;
;     char* V_lds = lds; char* K_lds = lds + 2 * SHM_V; float* B_lds = (float*)(lds + 2 * SHM_V + 2 * SHM_K + NW * 64 * 4);
;     float* ws = (float*)(lds + 2 * SHM_V + 2 * SHM_K) + wid * 64; float* li_l = ws, * al_l = ws + 32;
;     float m_reg = -1e30f, l_reg = 0; f32x16 o[4] = {};
;     const int sr = tid >> 4, sc = (tid & 15) * 8, vst0 = v_st(sr, sc), vst1 = v_st(32 + sr, sc), kws = KSWZ(sr, sc * 2);
;     const int vb0 = (int)(uintptr_t)V_lds + v_rd_base(lane);
;     const TIn* Kh = cur.K; const TIn* Vh = cur.V; const float* Ch = cur.CB;
;     ...
;     constexpr int NQL = F32 ? 16 : 8;
;     constexpr bool SK = WSKIP && !F32;
;     ...
;     f32x16 pA0, pA1, pB0, pB1; float mnA, mnB, alA, alB; bf16x8 pa0, pa1, pa2, pa3;
;     if constexpr (F32) { VMW(); SWRITE_VF(0); SBAR(); } else { SWRITE_HV(0); SBAR(); }
;     if (NT > 1) { if constexpr (F32) SLOAD_F((const float*)Kh, KBASE(1)); else SLOAD_H(Kh, Vh, Ch, KBASE(1)); }
.LBB0_1237:
	s_getreg_b32 s2, hwreg(HW_REG_HW_ID, 0, 6)
	s_and_b32 s2, s2, 63
	s_lshl_b32 s2, s2, 2
	s_add_i32 s2, s2, 0
	s_add_i32 s2, s2, 0x23e00
	v_mov_b32_e32 v0, s2
	ds_read_b32 v0, v0
	s_add_i32 s2, s57, 0xfffff001
	s_lshr_b32 s2, s2, 6
	v_mbcnt_lo_u32_b32 v218, -1, 0
	s_cmpk_gt_i32 s57, 0xfff
	s_waitcnt lgkmcnt(0)
	v_readfirstlane_b32 s3, v0
	v_mbcnt_hi_u32_b32 v218, -1, v218
	s_cselect_b32 s28, s2, 0
	s_lshr_b32 s100, s3, 2
	s_ashr_i32 s2, s57, 31
	v_lshl_add_u32 v34, s3, 6, v218
	v_ashrrev_i32_e32 v230, 4, v34
	s_lshr_b32 s2, s2, 26
	v_add_u32_e32 v231, 32, v230
	s_add_i32 s2, s2, s57
	v_and_b32_e32 v2, 0xfffff0, v230
	v_lshlrev_b32_e32 v3, 1, v230
	v_and_b32_e32 v5, 0xfffff0, v231
	v_lshlrev_b32_e32 v6, 1, v231
	s_addk_i32 s2, 0xff
	v_lshlrev_b32_e32 v0, 3, v218
	v_and_or_b32 v2, v3, 8, v2
	v_and_or_b32 v5, v6, 8, v5
	s_ashr_i32 s2, s2, 6
	v_and_b32_e32 v229, 0x78, v0
	v_lshrrev_b32_e32 v3, 1, v230
	v_lshrrev_b32_e32 v2, 1, v2
	v_bfe_u32 v0, v0, 5, 2
	v_and_b32_e32 v4, 3, v230
	v_lshrrev_b32_e32 v5, 1, v5
	s_add_i32 s2, s2, 1
	v_or_b32_e32 v2, v2, v0
	v_and_or_b32 v3, v3, 4, v4
	v_lshlrev_b32_e32 v35, 1, v229
	v_or_b32_e32 v0, v5, v0
	s_cmpk_lt_i32 s57, 0xf01
	v_lshlrev_b32_e32 v2, 9, v2
	v_lshlrev_b32_e32 v3, 6, v3
	v_and_b32_e32 v4, 48, v35
	v_lshlrev_b32_e32 v0, 9, v0
	s_cselect_b32 s56, s2, 64
	v_or3_b32 v2, v2, v3, v4
	v_or3_b32 v0, v0, v3, v4
	v_mov_b32_e32 v228, v234
	v_readfirstlane_b32 s29, v34
	s_sub_i32 s59, s56, s28
	v_add_u32_e32 v237, 0, v2
	v_add_u32_e32 v238, 0, v0
	s_waitcnt vmcnt(0)
	ds_write_b128 v237, v[124:127]
	ds_write_b128 v238, v[112:115]
	s_cmp_gt_i32 s59, 1
	s_cselect_b64 s[4:5], -1, 0
	s_lshl_b32 s68, s28, 6
	v_lshlrev_b32_e32 v0, 5, v218
	s_cmp_lt_i32 s59, 2
	v_and_b32_e32 v219, 32, v0
	s_cbranch_scc1 .LBB0_1239
	s_or_b32 s2, s68, 64
	v_add_u32_e32 v4, s2, v230
	v_add_u32_e32 v0, v4, v219
	v_lshl_add_u64 v[2:3], v[0:1], 2, s[66:67]
	v_lshl_or_b32 v0, v4, 11, v229
	global_load_dword v176, v[2:3], off
	v_lshlrev_b64 v[2:3], 1, v[0:1]
	v_add_u32_e32 v0, s2, v231
	v_lshl_or_b32 v0, v0, 11, v229
	v_lshl_add_u64 v[4:5], s[64:65], 0, v[2:3]
	v_lshlrev_b64 v[6:7], 1, v[0:1]
	v_lshl_add_u64 v[2:3], s[62:63], 0, v[2:3]
	v_lshl_add_u64 v[8:9], s[64:65], 0, v[6:7]
	global_load_dwordx4 v[124:127], v[4:5], off
	global_load_dwordx4 v[112:115], v[8:9], off
	v_lshl_add_u64 v[4:5], s[62:63], 0, v[6:7]
	global_load_dwordx4 v[116:119], v[2:3], off
	global_load_dwordx4 v[120:123], v[4:5], off

; __device__ __forceinline__ void partialSM(f32x16& p0, f32x16& p1, float& m_reg, float& mn, float& alpha) {
;     ...
;     constexpr float C2 = 1.4426950408889634f * SCALE;
;     if (__builtin_expect(__all((pmax - m_reg) * SCALE <= THR), 1)) { mn = m_reg; alpha = 1.f; }
;     else { mn = fmaxf(m_reg, pmax); alpha = __builtin_amdgcn_exp2f((m_reg - mn) * C2); m_reg = mn; }
;     const float mnL = -mn * C2;
;     for (int r = 0; r < 16; ++r) p0[r] = fmaf(p0[r], C2, mnL); for (int r = 0; r < 16; ++r) p1[r] = fmaf(p1[r], C2, mnL);
;     for (int r = 0; r < 16; ++r) p0[r] = __builtin_amdgcn_exp2f(p0[r]);
; template <class TIn, class TOut>
; __device__ __forceinline__ void causal_swa_block(const BlockRef<TIn, TOut>& cur, const BlockRef<TIn, TOut>& nxt, int skv, int W, char* lds, Seam<TIn>& S) {
;     ...
;     for (int t = 1; t + 1 < NT; t += 2) {
.LBB0_1246:
	s_cmp_eq_u32 s100, 0
	s_cbranch_scc1 .Lattn_h1_blk_after
	v_cndmask_b32_e64 v180, v2, v247, s[4:5]
	v_mul_f32_e32 v2, 0xbe0293ee, v180
	s_waitcnt vmcnt(1)
	v_fmamk_f32 v13, v138, 0x3e0293ee, v2
	v_fmamk_f32 v138, v139, 0x3e0293ee, v2
	v_fmamk_f32 v139, v140, 0x3e0293ee, v2
	v_fmamk_f32 v140, v141, 0x3e0293ee, v2
	v_fmamk_f32 v141, v142, 0x3e0293ee, v2
	v_mov_b32_e32 v142, v2
	v_fmamk_f32 v3, v128, 0x3e0293ee, v2
	v_fmamk_f32 v4, v129, 0x3e0293ee, v2
	v_fmamk_f32 v5, v130, 0x3e0293ee, v2
	v_fmamk_f32 v6, v131, 0x3e0293ee, v2
	v_fmamk_f32 v7, v132, 0x3e0293ee, v2
	v_fmamk_f32 v8, v133, 0x3e0293ee, v2
	v_fmamk_f32 v9, v134, 0x3e0293ee, v2
	v_fmamk_f32 v10, v135, 0x3e0293ee, v2
	v_fmamk_f32 v11, v136, 0x3e0293ee, v2
	v_fmamk_f32 v12, v137, 0x3e0293ee, v2
	v_fmac_f32_e32 v142, 0x3e0293ee, v143
	v_exp_f32_e32 v191, v3
	v_exp_f32_e32 v193, v4
	v_exp_f32_e32 v189, v5
	v_exp_f32_e32 v192, v6
	v_exp_f32_e32 v188, v7
	v_exp_f32_e32 v190, v8
	v_exp_f32_e32 v186, v9
	v_exp_f32_e32 v187, v10
	v_exp_f32_e32 v182, v11
	v_exp_f32_e32 v185, v12
	s_waitcnt vmcnt(0)
	v_exp_f32_e32 v179, v13
	v_exp_f32_e32 v183, v138
	v_exp_f32_e32 v177, v139
	v_exp_f32_e32 v184, v140
	v_exp_f32_e32 v178, v141
	v_exp_f32_e32 v181, v142
	v_pk_fma_f32 v[128:129], v[126:127], s[44:45], v[2:3] op_sel_hi:[1,0,0]
	v_pk_fma_f32 v[130:131], v[124:125], s[44:45], v[2:3] op_sel_hi:[1,0,0]
	v_pk_fma_f32 v[132:133], v[122:123], s[44:45], v[2:3] op_sel_hi:[1,0,0]
	v_pk_fma_f32 v[134:135], v[120:121], s[44:45], v[2:3] op_sel_hi:[1,0,0]
	v_pk_fma_f32 v[136:137], v[118:119], s[44:45], v[2:3] op_sel_hi:[1,0,0]
	v_pk_fma_f32 v[138:139], v[116:117], s[44:45], v[2:3] op_sel_hi:[1,0,0]
	v_pk_fma_f32 v[140:141], v[114:115], s[44:45], v[2:3] op_sel_hi:[1,0,0]
	v_pk_fma_f32 v[142:143], v[112:113], s[44:45], v[2:3] op_sel_hi:[1,0,0]
	v_add_f32_e32 v2, v244, v245
	v_fmac_f32_e32 v2, v240, v241
	v_add_f32_e32 v241, v249, v250
	s_addk_i32 s68, 0x80
	s_add_i32 s61, s61, 2
	v_fmac_f32_e32 v241, v2, v15
	v_add_u32_e32 v243, 0xffffff80, v243
	s_cmp_ge_i32 s61, s59
	v_add_u32_e32 v14, 0x40000, v14
	v_mov_b32_e32 v240, v0
	s_waitcnt lgkmcnt(0)
	s_barrier
	s_branch .Lattn_h1_blk_done

; template <class TIn, class TOut>
; __device__ __forceinline__ void causal_swa_block(const BlockRef<TIn, TOut>& cur, const BlockRef<TIn, TOut>& nxt, int skv, int W, char* lds, Seam<TIn>& S) {
;     ...
;     for (int t = 1; t + 1 < NT; t += 2) {
.Lattn_h1_blk_done:
	s_cbranch_scc1 .LBB0_1263

; __device__ __forceinline__ void partialSM(f32x16& p0, f32x16& p1, float& m_reg, float& mn, float& alpha) {
;     ...
;     constexpr float C2 = 1.4426950408889634f * SCALE;
;     if (__builtin_expect(__all((pmax - m_reg) * SCALE <= THR), 1)) { mn = m_reg; alpha = 1.f; }
;     else { mn = fmaxf(m_reg, pmax); alpha = __builtin_amdgcn_exp2f((m_reg - mn) * C2); m_reg = mn; }
;     const float mnL = -mn * C2;
;     for (int r = 0; r < 16; ++r) p0[r] = fmaf(p0[r], C2, mnL); for (int r = 0; r < 16; ++r) p1[r] = fmaf(p1[r], C2, mnL);
;     for (int r = 0; r < 16; ++r) p0[r] = __builtin_amdgcn_exp2f(p0[r]);
.LBB0_1253:
	s_cmp_eq_u32 s100, 0
	s_cbranch_scc1 .Lattn_h2_blk_after
	v_cndmask_b32_e64 v247, v0, v180, s[4:5]
	v_mul_f32_e32 v0, 0xbe0293ee, v247
	v_fmamk_f32 v80, v100, 0x3e0293ee, v0
	v_fmamk_f32 v81, v101, 0x3e0293ee, v0
	v_fmamk_f32 v82, v102, 0x3e0293ee, v0
	v_fmamk_f32 v83, v103, 0x3e0293ee, v0
	v_fmamk_f32 v116, v104, 0x3e0293ee, v0
	v_fmamk_f32 v117, v105, 0x3e0293ee, v0
	v_fmamk_f32 v118, v106, 0x3e0293ee, v0
	v_fmamk_f32 v119, v107, 0x3e0293ee, v0
	v_fmamk_f32 v120, v108, 0x3e0293ee, v0
	v_fmamk_f32 v121, v109, 0x3e0293ee, v0
	v_fmamk_f32 v122, v110, 0x3e0293ee, v0
	v_fmamk_f32 v123, v111, 0x3e0293ee, v0
	v_fmamk_f32 v112, v112, 0x3e0293ee, v0
	v_fmamk_f32 v113, v113, 0x3e0293ee, v0
	v_fmamk_f32 v114, v114, 0x3e0293ee, v0
	v_fmamk_f32 v115, v115, 0x3e0293ee, v0
	v_fmamk_f32 v100, v84, 0x3e0293ee, v0
	v_fmamk_f32 v109, v85, 0x3e0293ee, v0
	v_fmamk_f32 v110, v86, 0x3e0293ee, v0
	v_fmamk_f32 v111, v87, 0x3e0293ee, v0
	v_fmamk_f32 v180, v88, 0x3e0293ee, v0
	v_fmamk_f32 v101, v89, 0x3e0293ee, v0
	v_fmamk_f32 v102, v90, 0x3e0293ee, v0
	v_fmamk_f32 v103, v91, 0x3e0293ee, v0
	v_fmamk_f32 v104, v92, 0x3e0293ee, v0
	v_fmamk_f32 v105, v93, 0x3e0293ee, v0
	v_fmamk_f32 v106, v94, 0x3e0293ee, v0
	v_fmamk_f32 v107, v95, 0x3e0293ee, v0
	v_exp_f32_e32 v80, v80
	v_exp_f32_e32 v81, v81
	v_exp_f32_e32 v82, v82
	v_exp_f32_e32 v83, v83
	v_exp_f32_e32 v84, v116
	v_exp_f32_e32 v85, v117
	v_exp_f32_e32 v86, v118
	v_exp_f32_e32 v87, v119
	v_exp_f32_e32 v88, v120
	v_exp_f32_e32 v89, v121
	v_exp_f32_e32 v90, v122
	v_exp_f32_e32 v91, v123
	v_exp_f32_e32 v92, v112
	v_exp_f32_e32 v93, v113
	v_exp_f32_e32 v94, v114
	v_exp_f32_e32 v95, v115
	v_fmamk_f32 v108, v96, 0x3e0293ee, v0
	v_fmamk_f32 v181, v97, 0x3e0293ee, v0
	v_fmamk_f32 v182, v98, 0x3e0293ee, v0
	v_fmac_f32_e32 v0, 0x3e0293ee, v99
	s_waitcnt lgkmcnt(0)
	s_barrier
	s_branch .Lattn_h2_blk_done

.Lattn_h2_blk_done:
	s_add_i32 s4, s61, 1
	s_cmp_lt_i32 s4, s59
	s_cselect_b64 s[28:29], -1, 0
	s_cmp_ge_i32 s4, s59
	s_cbranch_scc1 .Lattn_h2_noload
	v_add_u32_e32 v200, 0x41, v248
	v_lshl_add_u64 v[2:3], v[200:201], 2, s[66:67]
	v_add_u32_e32 v200, 0x20000, v14
	v_lshlrev_b64 v[10:11], 1, v[200:201]
	v_add_u32_e32 v200, 0x30000, v14
	v_lshlrev_b64 v[12:13], 1, v[200:201]
	global_load_dword v246, v[2:3], off
	v_lshl_add_u64 v[2:3], s[64:65], 0, v[10:11]
	v_lshl_add_u64 v[6:7], s[64:65], 0, v[12:13]
	v_lshl_add_u64 v[10:11], s[62:63], 0, v[10:11]
	v_lshl_add_u64 v[176:177], s[62:63], 0, v[12:13]
	global_load_dwordx4 v[2:5], v[2:3], off
	s_nop 0
	global_load_dwordx4 v[6:9], v[6:7], off
	s_nop 0
	global_load_dwordx4 v[10:13], v[10:11], off
	s_nop 0
	global_load_dwordx4 v[176:179], v[176:177], off

; __global__ void __launch_bounds__(512, 2) fwd_megakernel(ArgsS args_unused) {
	.amdhsa_kernel _Z14fwd_megakernel5ArgsS
		.amdhsa_group_segment_fixed_size 0
		.amdhsa_private_segment_fixed_size 0
		.amdhsa_kernarg_size 432
		.amdhsa_user_sgpr_count 2
		.amdhsa_user_sgpr_dispatch_ptr 0
		.amdhsa_user_sgpr_queue_ptr 0
		.amdhsa_user_sgpr_kernarg_segment_ptr 1
		.amdhsa_user_sgpr_dispatch_id 0
		.amdhsa_user_sgpr_kernarg_preload_length 0
		.amdhsa_user_sgpr_kernarg_preload_offset 0
		.amdhsa_user_sgpr_private_segment_size 0
		.amdhsa_uses_dynamic_stack 0
		.amdhsa_enable_private_segment 0
		.amdhsa_system_sgpr_workgroup_id_x 1
		.amdhsa_system_sgpr_workgroup_id_y 0
		.amdhsa_system_sgpr_workgroup_id_z 0
		.amdhsa_system_sgpr_workgroup_info 0
		.amdhsa_system_vgpr_workitem_id 2
		.amdhsa_next_free_vgpr 256
		.amdhsa_next_free_sgpr 102
		.amdhsa_accum_offset 256
		.amdhsa_reserve_vcc 1
		.amdhsa_float_round_mode_32 0
		.amdhsa_float_round_mode_16_64 0
		.amdhsa_float_denorm_mode_32 3
		.amdhsa_float_denorm_mode_16_64 3
		.amdhsa_dx10_clamp 1
		.amdhsa_ieee_mode 1
		.amdhsa_fp16_overflow 0
		.amdhsa_tg_split 0
		.amdhsa_exception_fp_ieee_invalid_op 0
		.amdhsa_exception_fp_denorm_src 0
		.amdhsa_exception_fp_ieee_div_zero 0
		.amdhsa_exception_fp_ieee_overflow 0
		.amdhsa_exception_fp_ieee_underflow 0
		.amdhsa_exception_fp_ieee_inexact 0
		.amdhsa_exception_int_div_zero 0
	.end_amdhsa_kernel

; __global__ void __launch_bounds__(512, 2) fwd_megakernel(ArgsS args_unused) {
amdhsa.kernels:
  - .agpr_count:     0
    .args:
      - .offset:         0
        .size:           176
        .value_kind:     by_value
      - .offset:         176
        .size:           4
        .value_kind:     hidden_block_count_x
      - .offset:         180
        .size:           4
        .value_kind:     hidden_block_count_y
      - .offset:         184
        .size:           4
        .value_kind:     hidden_block_count_z
      - .offset:         188
        .size:           2
        .value_kind:     hidden_group_size_x
      - .offset:         190
        .size:           2
        .value_kind:     hidden_group_size_y
      - .offset:         192
        .size:           2
        .value_kind:     hidden_group_size_z
      - .offset:         194
        .size:           2
        .value_kind:     hidden_remainder_x
      - .offset:         196
        .size:           2
        .value_kind:     hidden_remainder_y
      - .offset:         198
        .size:           2
        .value_kind:     hidden_remainder_z
      - .offset:         216
        .size:           8
        .value_kind:     hidden_global_offset_x
      - .offset:         224
        .size:           8
        .value_kind:     hidden_global_offset_y
      - .offset:         232
        .size:           8
        .value_kind:     hidden_global_offset_z
      - .offset:         240
        .size:           2
        .value_kind:     hidden_grid_dims
      - .offset:         264
        .size:           8
        .value_kind:     hidden_multigrid_sync_arg
      - .offset:         296
        .size:           4
        .value_kind:     hidden_dynamic_lds_size
    .group_segment_fixed_size: 0
    .kernarg_segment_align: 8
    .kernarg_segment_size: 432
    .language:       OpenCL C
    .language_version:
      - 2
      - 0
    .max_flat_workgroup_size: 512
    .name:           _Z14fwd_megakernel5ArgsS
    .private_segment_fixed_size: 0
    .sgpr_count:     108
    .sgpr_spill_count: 88
    .symbol:         _Z14fwd_megakernel5ArgsS.kd
    .uniform_work_group_size: 1
    .uses_dynamic_stack: false
    .vgpr_count:     256
    .vgpr_spill_count: 0
    .wavefront_size: 64
